# attention unit epilogue: normalise + bf16 pack, per-wave LDS transpose, 8 dwordx4 stores per lane instead of 64 two-byte stores
# speedup vs baseline: 1.0093x; 1.0093x over previous
.LBB0_467:
	s_or_b64 exec, exec, s[2:3]
	s_waitcnt lgkmcnt(0)
	v_add_u32_e32 v74, v179, v178
	ds_read_b128 v[66:69], v74
	ds_read_b128 v[70:73], v74 offset:32
	ds_read_b128 v[76:79], v74 offset:64
	ds_read_b128 v[80:83], v74 offset:96
	s_ashr_i32 s27, s26, 31
	s_lshl_b64 s[2:3], s[26:27], 12
	s_add_u32 s6, s14, s2
	s_addc_u32 s7, s15, s3
	s_lshl_b64 s[2:3], s[30:31], 1
	s_add_u32 s2, s6, s2
	s_addc_u32 s3, s7, s3
	s_lshl_b32 s6, s9, 13
	v_lshlrev_b32_e32 v84, 10, v180
	v_lshl_add_u32 v84, v181, 1, v84
	v_add_u32_e32 v84, s6, v84
	v_lshl_add_u32 v85, v180, 5, v181
	v_lshlrev_b32_e32 v86, 4, v85
	v_add_u32_e32 v86, s6, v86
	v_lshrrev_b32_e32 v87, 4, v85
	v_lshlrev_b32_e32 v87, 12, v87
	v_and_b32_e32 v88, 15, v85
	v_lshl_add_u32 v87, v88, 4, v87
	v_add_u32_e32 v88, 0x4000, v87
	v_add_u32_e32 v89, 0x8000, v87
	v_add_u32_e32 v90, 0xc000, v87
	v_add_u32_e32 v91, 0x10000, v87
	v_add_u32_e32 v92, 0x14000, v87
	v_add_u32_e32 v93, 0x18000, v87
	v_add_u32_e32 v94, 0x1c000, v87
	s_waitcnt lgkmcnt(0)
	v_rcp_f32_e32 v66, v66
	v_rcp_f32_e32 v67, v67
	v_rcp_f32_e32 v68, v68
	v_rcp_f32_e32 v69, v69
	v_rcp_f32_e32 v70, v70
	v_rcp_f32_e32 v71, v71
	v_rcp_f32_e32 v72, v72
	v_rcp_f32_e32 v73, v73
	v_rcp_f32_e32 v76, v76
	v_rcp_f32_e32 v77, v77
	v_rcp_f32_e32 v78, v78
	v_rcp_f32_e32 v79, v79
	v_rcp_f32_e32 v80, v80
	v_rcp_f32_e32 v81, v81
	v_rcp_f32_e32 v82, v82
	v_rcp_f32_e32 v83, v83
	s_barrier
	v_mul_f32_e32 v2, v2, v66
	v_mul_f32_e32 v50, v50, v66
	v_cvt_pk_bf16_f32 v2, v2, v50
	ds_write_b16 v84, v2 offset:0
	ds_write_b16_d16_hi v84, v2 offset:64
	v_mul_f32_e32 v34, v34, v66
	v_mul_f32_e32 v18, v18, v66
	v_cvt_pk_bf16_f32 v34, v34, v18
	ds_write_b16 v84, v34 offset:128
	ds_write_b16_d16_hi v84, v34 offset:192
	v_mul_f32_e32 v3, v3, v67
	v_mul_f32_e32 v51, v51, v67
	v_cvt_pk_bf16_f32 v3, v3, v51
	ds_write_b16 v84, v3 offset:256
	ds_write_b16_d16_hi v84, v3 offset:320
	v_mul_f32_e32 v35, v35, v67
	v_mul_f32_e32 v19, v19, v67
	v_cvt_pk_bf16_f32 v35, v35, v19
	ds_write_b16 v84, v35 offset:384
	ds_write_b16_d16_hi v84, v35 offset:448
	v_mul_f32_e32 v4, v4, v68
	v_mul_f32_e32 v52, v52, v68
	v_cvt_pk_bf16_f32 v4, v4, v52
	ds_write_b16 v84, v4 offset:512
	ds_write_b16_d16_hi v84, v4 offset:576
	v_mul_f32_e32 v36, v36, v68
	v_mul_f32_e32 v20, v20, v68
	v_cvt_pk_bf16_f32 v36, v36, v20
	ds_write_b16 v84, v36 offset:640
	ds_write_b16_d16_hi v84, v36 offset:704
	v_mul_f32_e32 v5, v5, v69
	v_mul_f32_e32 v53, v53, v69
	v_cvt_pk_bf16_f32 v5, v5, v53
	ds_write_b16 v84, v5 offset:768
	ds_write_b16_d16_hi v84, v5 offset:832
	v_mul_f32_e32 v37, v37, v69
	v_mul_f32_e32 v21, v21, v69
	v_cvt_pk_bf16_f32 v37, v37, v21
	ds_write_b16 v84, v37 offset:896
	ds_write_b16_d16_hi v84, v37 offset:960
	v_mul_f32_e32 v6, v6, v70
	v_mul_f32_e32 v54, v54, v70
	v_cvt_pk_bf16_f32 v6, v6, v54
	ds_write_b16 v84, v6 offset:2048
	ds_write_b16_d16_hi v84, v6 offset:2112
	v_mul_f32_e32 v38, v38, v70
	v_mul_f32_e32 v22, v22, v70
	v_cvt_pk_bf16_f32 v38, v38, v22
	ds_write_b16 v84, v38 offset:2176
	ds_write_b16_d16_hi v84, v38 offset:2240
	v_mul_f32_e32 v7, v7, v71
	v_mul_f32_e32 v55, v55, v71
	v_cvt_pk_bf16_f32 v7, v7, v55
	ds_write_b16 v84, v7 offset:2304
	ds_write_b16_d16_hi v84, v7 offset:2368
	v_mul_f32_e32 v39, v39, v71
	v_mul_f32_e32 v23, v23, v71
	v_cvt_pk_bf16_f32 v39, v39, v23
	ds_write_b16 v84, v39 offset:2432
	ds_write_b16_d16_hi v84, v39 offset:2496
	v_mul_f32_e32 v8, v8, v72
	v_mul_f32_e32 v56, v56, v72
	v_cvt_pk_bf16_f32 v8, v8, v56
	ds_write_b16 v84, v8 offset:2560
	ds_write_b16_d16_hi v84, v8 offset:2624
	v_mul_f32_e32 v40, v40, v72
	v_mul_f32_e32 v24, v24, v72
	v_cvt_pk_bf16_f32 v40, v40, v24
	ds_write_b16 v84, v40 offset:2688
	ds_write_b16_d16_hi v84, v40 offset:2752
	v_mul_f32_e32 v9, v9, v73
	v_mul_f32_e32 v57, v57, v73
	v_cvt_pk_bf16_f32 v9, v9, v57
	ds_write_b16 v84, v9 offset:2816
	ds_write_b16_d16_hi v84, v9 offset:2880
	v_mul_f32_e32 v41, v41, v73
	v_mul_f32_e32 v25, v25, v73
	v_cvt_pk_bf16_f32 v41, v41, v25
	ds_write_b16 v84, v41 offset:2944
	ds_write_b16_d16_hi v84, v41 offset:3008
	v_mul_f32_e32 v10, v10, v76
	v_mul_f32_e32 v58, v58, v76
	v_cvt_pk_bf16_f32 v10, v10, v58
	ds_write_b16 v84, v10 offset:4096
	ds_write_b16_d16_hi v84, v10 offset:4160
	v_mul_f32_e32 v42, v42, v76
	v_mul_f32_e32 v26, v26, v76
	v_cvt_pk_bf16_f32 v42, v42, v26
	ds_write_b16 v84, v42 offset:4224
	ds_write_b16_d16_hi v84, v42 offset:4288
	v_mul_f32_e32 v11, v11, v77
	v_mul_f32_e32 v59, v59, v77
	v_cvt_pk_bf16_f32 v11, v11, v59
	ds_write_b16 v84, v11 offset:4352
	ds_write_b16_d16_hi v84, v11 offset:4416
	v_mul_f32_e32 v43, v43, v77
	v_mul_f32_e32 v27, v27, v77
	v_cvt_pk_bf16_f32 v43, v43, v27
	ds_write_b16 v84, v43 offset:4480
	ds_write_b16_d16_hi v84, v43 offset:4544
	v_mul_f32_e32 v12, v12, v78
	v_mul_f32_e32 v60, v60, v78
	v_cvt_pk_bf16_f32 v12, v12, v60
	ds_write_b16 v84, v12 offset:4608
	ds_write_b16_d16_hi v84, v12 offset:4672
	v_mul_f32_e32 v44, v44, v78
	v_mul_f32_e32 v28, v28, v78
	v_cvt_pk_bf16_f32 v44, v44, v28
	ds_write_b16 v84, v44 offset:4736
	ds_write_b16_d16_hi v84, v44 offset:4800
	v_mul_f32_e32 v13, v13, v79
	v_mul_f32_e32 v61, v61, v79
	v_cvt_pk_bf16_f32 v13, v13, v61
	ds_write_b16 v84, v13 offset:4864
	ds_write_b16_d16_hi v84, v13 offset:4928
	v_mul_f32_e32 v45, v45, v79
	v_mul_f32_e32 v29, v29, v79
	v_cvt_pk_bf16_f32 v45, v45, v29
	ds_write_b16 v84, v45 offset:4992
	ds_write_b16_d16_hi v84, v45 offset:5056
	v_mul_f32_e32 v14, v14, v80
	v_mul_f32_e32 v62, v62, v80
	v_cvt_pk_bf16_f32 v14, v14, v62
	ds_write_b16 v84, v14 offset:6144
	ds_write_b16_d16_hi v84, v14 offset:6208
	v_mul_f32_e32 v46, v46, v80
	v_mul_f32_e32 v30, v30, v80
	v_cvt_pk_bf16_f32 v46, v46, v30
	ds_write_b16 v84, v46 offset:6272
	ds_write_b16_d16_hi v84, v46 offset:6336
	v_mul_f32_e32 v15, v15, v81
	v_mul_f32_e32 v63, v63, v81
	v_cvt_pk_bf16_f32 v15, v15, v63
	ds_write_b16 v84, v15 offset:6400
	ds_write_b16_d16_hi v84, v15 offset:6464
	v_mul_f32_e32 v47, v47, v81
	v_mul_f32_e32 v31, v31, v81
	v_cvt_pk_bf16_f32 v47, v47, v31
	ds_write_b16 v84, v47 offset:6528
	ds_write_b16_d16_hi v84, v47 offset:6592
	v_mul_f32_e32 v16, v16, v82
	v_mul_f32_e32 v64, v64, v82
	v_cvt_pk_bf16_f32 v16, v16, v64
	ds_write_b16 v84, v16 offset:6656
	ds_write_b16_d16_hi v84, v16 offset:6720
	v_mul_f32_e32 v48, v48, v82
	v_mul_f32_e32 v32, v32, v82
	v_cvt_pk_bf16_f32 v48, v48, v32
	ds_write_b16 v84, v48 offset:6784
	ds_write_b16_d16_hi v84, v48 offset:6848
	v_mul_f32_e32 v17, v17, v83
	v_mul_f32_e32 v65, v65, v83
	v_cvt_pk_bf16_f32 v17, v17, v65
	ds_write_b16 v84, v17 offset:6912
	ds_write_b16_d16_hi v84, v17 offset:6976
	v_mul_f32_e32 v49, v49, v83
	v_mul_f32_e32 v33, v33, v83
	v_cvt_pk_bf16_f32 v49, v49, v33
	ds_write_b16 v84, v49 offset:7040
	ds_write_b16_d16_hi v84, v49 offset:7104
	s_waitcnt lgkmcnt(0)
	ds_read_b128 v[2:5], v86 offset:0
	ds_read_b128 v[6:9], v86 offset:1024
	ds_read_b128 v[10:13], v86 offset:2048
	ds_read_b128 v[14:17], v86 offset:3072
	ds_read_b128 v[18:21], v86 offset:4096
	ds_read_b128 v[22:25], v86 offset:5120
	ds_read_b128 v[26:29], v86 offset:6144
	ds_read_b128 v[30:33], v86 offset:7168
	s_waitcnt lgkmcnt(7)
	global_store_dwordx4 v87, v[2:5], s[2:3]
	s_waitcnt lgkmcnt(6)
	global_store_dwordx4 v88, v[6:9], s[2:3]
	s_waitcnt lgkmcnt(5)
	global_store_dwordx4 v89, v[10:13], s[2:3]
	s_waitcnt lgkmcnt(4)
	global_store_dwordx4 v90, v[14:17], s[2:3]
	s_waitcnt lgkmcnt(3)
	global_store_dwordx4 v91, v[18:21], s[2:3]
	s_waitcnt lgkmcnt(2)
	global_store_dwordx4 v92, v[22:25], s[2:3]
	s_waitcnt lgkmcnt(1)
	global_store_dwordx4 v93, v[26:29], s[2:3]
	s_waitcnt lgkmcnt(0)
	global_store_dwordx4 v94, v[30:33], s[2:3]
	s_waitcnt vmcnt(63) expcnt(7) lgkmcnt(15)
	s_barrier
